# qkv(0): ffn_out layer-2 weight transposes (176 tiles) done by the GEMM workgroups after their tile with a hand-written LDS transpose; idle workgroups convert fewer tiles
# speedup vs baseline: 1.0081x; 1.0081x over previous
.LBB0_505:
	s_and_b64 s[0:1], s[0:1], exec
	s_movk_i32 s0, 0x510
	s_cselect_b32 s28, s0, 0xa10
	s_movk_i32 s0, 0x620
	s_cselect_b32 s30, s0, 0xb80
	s_add_i32 s33, s33, s28
	v_mov_b32_e32 v32, v156
	s_cmp_ge_i32 s33, s30
	s_cbranch_scc1 .LBB0_664
	s_cmpk_gt_i32 s33, 0x15f
	s_mov_b64 s[24:25], -1
	s_cbranch_scc0 .LBB0_577
	s_cmpk_gt_u32 s33, 0x20f
	s_cbranch_scc0 .LBB0_574
	s_cmpk_gt_u32 s33, 0x28f
	s_cbranch_scc0 .LBB0_571
	s_cmpk_gt_u32 s33, 0x2cf
	s_cbranch_scc0 .LBB0_568
	s_cmpk_gt_u32 s33, 0x30f
	s_cbranch_scc0 .LBB0_565
	s_cmpk_gt_u32 s33, 0x36f
	s_cbranch_scc0 .LBB0_562
	s_cmpk_gt_u32 s33, 0x3af
	s_cbranch_scc0 .LBB0_559
	s_cmpk_gt_u32 s33, 0x50f
	s_cbranch_scc0 .LBB0_556
	s_cmpk_gt_u32 s33, 0x5bf
	s_cbranch_scc0 .LBB0_553
	s_cmpk_gt_u32 s33, 0x61f
	s_cbranch_scc0 .LBB0_550
	s_cmpk_gt_u32 s33, 0x6cf
	s_cbranch_scc0 .LBB0_547
	s_cmpk_gt_u32 s33, 0x70f
	s_cbranch_scc0 .LBB0_544
	s_cmpk_gt_u32 s33, 0x78f
	s_cbranch_scc0 .LBB0_541
	s_cmpk_gt_u32 s33, 0x7cf
	s_cbranch_scc0 .LBB0_538
	s_cmpk_gt_u32 s33, 0x8cf
	s_cbranch_scc0 .LBB0_535
	s_cmpk_gt_u32 s33, 0x92f
	s_cbranch_scc0 .LBB0_532
	s_cmpk_gt_u32 s33, 0x96f
	s_cbranch_scc0 .LBB0_529
	s_cmpk_gt_u32 s33, 0xacf
	s_mov_b64 s[4:5], -1
	s_cbranch_scc0 .LBB0_525
	s_load_dwordx2 s[0:1], s[72:73], 0xd8
	s_add_i32 s31, s33, 0xfffff530
	s_mov_b64 s[4:5], 0
	s_waitcnt lgkmcnt(0)
	s_add_u32 s0, s0, 0x2100000
	s_addc_u32 s1, s1, 0

.Lwh_entry:
	s_cmp_lg_u32 s54, 8
	s_cbranch_scc1 .LBB0_664
	s_cmpk_gt_i32 s0, 0xaf
	s_cbranch_scc1 .LBB0_664
	s_mov_b64 exec, -1
	s_waitcnt vmcnt(0) lgkmcnt(0)
	s_barrier
	s_lshr_b32 s4, s0, 4
	s_and_b32 s5, s0, 15
	s_load_dwordx2 s[24:25], s[72:73], 0xd8
	s_lshl_b32 s28, s4, 20
	s_lshl_b32 s29, s5, 8
	s_add_u32 s28, s28, s29
	s_add_u32 s28, s28, 0x1600000
	s_waitcnt lgkmcnt(0)
	s_add_u32 s24, s24, s28
	s_addc_u32 s25, s25, 0
	v_lshrrev_b32_e32 v40, 4, v156
	v_and_b32_e32 v41, 15, v156
	v_lshlrev_b32_e32 v41, 4, v41
	v_lshl_add_u32 v42, v40, 12, v41
	global_load_dwordx4 v[0:3], v42, s[24:25] nt
	s_add_u32 s24, s24, 0x20000
	s_addc_u32 s25, s25, 0
	global_load_dwordx4 v[4:7], v42, s[24:25] nt
	s_add_u32 s24, s24, 0x20000
	s_addc_u32 s25, s25, 0
	global_load_dwordx4 v[8:11], v42, s[24:25] nt
	s_add_u32 s24, s24, 0x20000
	s_addc_u32 s25, s25, 0
	global_load_dwordx4 v[12:15], v42, s[24:25] nt
	s_add_u32 s24, s24, 0x20000
	s_addc_u32 s25, s25, 0
	global_load_dwordx4 v[16:19], v42, s[24:25] nt
	s_add_u32 s24, s24, 0x20000
	s_addc_u32 s25, s25, 0
	global_load_dwordx4 v[20:23], v42, s[24:25] nt
	s_add_u32 s24, s24, 0x20000
	s_addc_u32 s25, s25, 0
	global_load_dwordx4 v[24:27], v42, s[24:25] nt
	s_add_u32 s24, s24, 0x20000
	s_addc_u32 s25, s25, 0
	global_load_dwordx4 v[28:31], v42, s[24:25] nt
	v_mul_u32_u24_e32 v43, 0x104, v40
	v_add_u32_e32 v43, v43, v41
	s_waitcnt vmcnt(7)
	ds_write2_b32 v43, v0, v1 offset1:1
	ds_write2_b32 v43, v2, v3 offset0:2 offset1:3
	v_add_u32_e32 v43, 0x2080, v43
	s_waitcnt vmcnt(6)
	ds_write2_b32 v43, v4, v5 offset1:1
	ds_write2_b32 v43, v6, v7 offset0:2 offset1:3
	v_add_u32_e32 v43, 0x2080, v43
	s_waitcnt vmcnt(5)
	ds_write2_b32 v43, v8, v9 offset1:1
	ds_write2_b32 v43, v10, v11 offset0:2 offset1:3
	v_add_u32_e32 v43, 0x2080, v43
	s_waitcnt vmcnt(4)
	ds_write2_b32 v43, v12, v13 offset1:1
	ds_write2_b32 v43, v14, v15 offset0:2 offset1:3
	v_add_u32_e32 v43, 0x2080, v43
	s_waitcnt vmcnt(3)
	ds_write2_b32 v43, v16, v17 offset1:1
	ds_write2_b32 v43, v18, v19 offset0:2 offset1:3
	v_add_u32_e32 v43, 0x2080, v43
	s_waitcnt vmcnt(2)
	ds_write2_b32 v43, v20, v21 offset1:1
	ds_write2_b32 v43, v22, v23 offset0:2 offset1:3
	v_add_u32_e32 v43, 0x2080, v43
	s_waitcnt vmcnt(1)
	ds_write2_b32 v43, v24, v25 offset1:1
	ds_write2_b32 v43, v26, v27 offset0:2 offset1:3
	v_add_u32_e32 v43, 0x2080, v43
	s_waitcnt vmcnt(0)
	ds_write2_b32 v43, v28, v29 offset1:1
	ds_write2_b32 v43, v30, v31 offset0:2 offset1:3
	s_waitcnt lgkmcnt(0)
	s_barrier
	v_lshrrev_b32_e32 v40, 3, v156
	v_and_b32_e32 v41, 7, v156
	v_mul_u32_u24_e32 v45, 0x820, v41
	v_lshl_add_u32 v45, v40, 2, v45
	v_and_b32_e32 v46, 32, v40
	v_bfe_u32 v47, v40, 2, 1
	v_lshl_add_u32 v46, v47, 4, v46
	v_bfe_u32 v47, v40, 3, 2
	v_lshl_add_u32 v46, v47, 2, v46
	v_and_b32_e32 v47, 3, v40
	v_add_u32_e32 v46, v46, v47
	v_mul_u32_u24_e32 v46, 0x1600, v46
	v_lshl_add_u32 v46, v41, 4, v46
	s_mul_i32 s28, s5, 0x58000
	s_lshl_b32 s29, s4, 9
	s_add_u32 s28, s28, s29
	s_add_u32 s28, s28, 0x5104000
	s_add_u32 s24, s48, s28
	s_addc_u32 s25, s49, 0
	v_add_u32_e32 v48, 0x0, v45
	ds_read2_b32 v[32:33], v48 offset1:65
	ds_read2_b32 v[34:35], v48 offset0:130 offset1:195
	v_add_u32_e32 v49, 0x410, v48
	ds_read2_b32 v[36:37], v49 offset1:65
	ds_read2_b32 v[38:39], v49 offset0:130 offset1:195
	s_waitcnt lgkmcnt(0)
	v_cvt_pk_bf16_f32 v32, v32, v33
	v_cvt_pk_bf16_f32 v33, v34, v35
	v_cvt_pk_bf16_f32 v34, v36, v37
	v_cvt_pk_bf16_f32 v35, v38, v39
	global_store_dwordx4 v46, v[32:35], s[24:25]
	s_nop 1
	v_add_u32_e32 v48, 0x4100, v45
	ds_read2_b32 v[32:33], v48 offset1:65
	ds_read2_b32 v[34:35], v48 offset0:130 offset1:195
	v_add_u32_e32 v49, 0x410, v48
	ds_read2_b32 v[36:37], v49 offset1:65
	ds_read2_b32 v[38:39], v49 offset0:130 offset1:195
	s_waitcnt lgkmcnt(0)
	v_cvt_pk_bf16_f32 v32, v32, v33
	v_cvt_pk_bf16_f32 v33, v34, v35
	v_cvt_pk_bf16_f32 v34, v36, v37
	v_cvt_pk_bf16_f32 v35, v38, v39
	global_store_dwordx4 v46, v[32:35], s[24:25] offset:128
	s_nop 1
	v_add_u32_e32 v48, 0x8200, v45
	ds_read2_b32 v[32:33], v48 offset1:65
	ds_read2_b32 v[34:35], v48 offset0:130 offset1:195
	v_add_u32_e32 v49, 0x410, v48
	ds_read2_b32 v[36:37], v49 offset1:65
	ds_read2_b32 v[38:39], v49 offset0:130 offset1:195
	s_waitcnt lgkmcnt(0)
	v_cvt_pk_bf16_f32 v32, v32, v33
	v_cvt_pk_bf16_f32 v33, v34, v35
	v_cvt_pk_bf16_f32 v34, v36, v37
	v_cvt_pk_bf16_f32 v35, v38, v39
	global_store_dwordx4 v46, v[32:35], s[24:25] offset:256
	s_nop 1
	v_add_u32_e32 v48, 0xc300, v45
	ds_read2_b32 v[32:33], v48 offset1:65
	ds_read2_b32 v[34:35], v48 offset0:130 offset1:195
	v_add_u32_e32 v49, 0x410, v48
	ds_read2_b32 v[36:37], v49 offset1:65
	ds_read2_b32 v[38:39], v49 offset0:130 offset1:195
	s_waitcnt lgkmcnt(0)
	v_cvt_pk_bf16_f32 v32, v32, v33
	v_cvt_pk_bf16_f32 v33, v34, v35
	v_cvt_pk_bf16_f32 v34, v36, v37
	v_cvt_pk_bf16_f32 v35, v38, v39
	global_store_dwordx4 v46, v[32:35], s[24:25] offset:384
	s_nop 1
	s_barrier
	s_branch .LBB0_664
